# P3 sample side: gMLP sample item loads its four LayerNorm rows together; GLU sample row block keeps the next iteration's loads in flight (vmcnt(10))
# speedup vs baseline: 1.0021x; 1.0021x over previous
; #define SGT_LOAD(S_, KS_) do { _Pragma("unroll") for (int u = 0; u < U; ++u) { a0[S_][u] = *(const bf16x8*)(ap + (KS_) + 32 * u); if (MB == 2) a1[S_][u] = *(const bf16x8*)(ap + (size_t)16 * lda + (KS_) + 32 * u); \
;         _Pragma("unroll") for (int n = 0; n < NBW; ++n) b[S_][u][n] = *(const bf16x8*)(bp + (size_t)n * 16 * K + (KS_) + 32 * u); } } while (0)
; #define SGT_MMA(S_) do { _Pragma("unroll") for (int u = 0; u < U; ++u) _Pragma("unroll") for (int n = 0; n < NBW; ++n) { acc[0][n] = __builtin_amdgcn_mfma_f32_16x16x32_bf16(b[S_][u][n], a0[S_][u], acc[0][n], 0, 0, 0); \
;         if (MB == 2) acc[MB - 1][n] = __builtin_amdgcn_mfma_f32_16x16x32_bf16(b[S_][u][n], a1[S_][u], acc[MB - 1][n], 0, 0, 0); } } while (0)
;     ...
;     constexpr bool ONEPASS = 16 * MB * (TN / 4) <= NWAVES * 64;
;     typename F::Pre pre{};
;     if constexpr (ONEPASS) { if (tid < 16 * MB * (TN / 4)) pre = f.prefetch(tid / (TN / 4), 4 * (tid % (TN / 4))); }
;     SGT_LOAD(0, 0);
; #pragma unroll 1
;     for (int ks = 0; ks < KPER; ks += 64 * U) {
;         if (ks + 32 * U < KPER) SGT_LOAD(1, ks + 32 * U);
;         SGT_MMA(0);
;         if (ks + 64 * U < KPER) SGT_LOAD(0, ks + 64 * U);
;         if (ks + 32 * U < KPER) SGT_MMA(1);
;     }
.Lglu_rb_b:
	v_mfma_f32_16x16x32_bf16 v[52:55], v[68:71], v[44:47], v[52:55]
	s_mov_b64 s[34:35], 0x100
	v_lshl_add_u64 v[124:125], v[124:125], 0, s[34:35]
	s_mov_b64 s[94:95], 0x100
	v_mfma_f32_16x16x32_bf16 v[68:71], v[80:83], v[44:47], v[76:79]
	v_lshl_add_u64 v[126:127], v[126:127], 0, s[34:35]
	s_and_b64 vcc, exec, s[14:15]
	v_mfma_f32_16x16x32_bf16 v[76:79], v[84:87], v[44:47], v[92:95]
	v_mfma_f32_16x16x32_bf16 v[80:83], v[88:91], v[44:47], v[96:99]
	v_mfma_f32_16x16x32_bf16 v[44:47], v[48:51], v[56:59], v[52:55]
	v_mfma_f32_16x16x32_bf16 v[52:55], v[64:67], v[56:59], v[68:71]
	v_mfma_f32_16x16x32_bf16 v[48:51], v[72:75], v[56:59], v[76:79]
	v_mfma_f32_16x16x32_bf16 v[56:59], v[60:63], v[56:59], v[80:83]
	s_cbranch_vccnz .LBB0_1066
.LBB0_1064:
	v_lshl_add_u64 v[130:131], v[124:125], 0, s[6:7]
	s_mov_b32 s14, 0x400000
	v_add_co_u32_e32 v64, vcc, s14, v130
	s_mov_b32 s14, 0x404000
	s_nop 0
	v_addc_co_u32_e32 v65, vcc, 0, v131, vcc
	s_waitcnt vmcnt(0)
	v_mfma_f32_16x16x32_bf16 v[44:47], v[12:15], v[4:7], v[44:47]
	v_add_co_u32_e32 v66, vcc, s14, v130
	s_mov_b32 s14, 0x408000
	s_nop 0
	v_addc_co_u32_e32 v67, vcc, 0, v131, vcc
	v_mfma_f32_16x16x32_bf16 v[60:63], v[20:23], v[4:7], v[52:55]
	v_add_co_u32_e32 v72, vcc, s14, v130
	v_lshl_add_u64 v[128:129], v[126:127], 0, s[6:7]
	v_mfma_f32_16x16x32_bf16 v[88:91], v[28:31], v[4:7], v[48:51]
	v_addc_co_u32_e32 v73, vcc, 0, v131, vcc
	s_mov_b32 s14, 0x40c000
	v_mfma_f32_16x16x32_bf16 v[96:99], v[36:39], v[4:7], v[56:59]
	v_add_co_u32_e32 v134, vcc, s14, v130
	s_addk_i32 s30, 0x80
	v_mfma_f32_16x16x32_bf16 v[52:55], v[16:19], v[8:11], v[44:47]
	s_nop 2
	global_load_dwordx4 v[44:47], v[128:129], off offset:-128
	global_load_dwordx4 v[56:59], v[128:129], off offset:-64
	global_load_dwordx4 v[68:71], v[64:65], off offset:128
	global_load_dwordx4 v[48:51], v[64:65], off offset:192
	global_load_dwordx4 v[80:83], v[66:67], off offset:128
	s_nop 0
	global_load_dwordx4 v[64:67], v[66:67], off offset:192
	s_nop 0
	global_load_dwordx4 v[84:87], v[72:73], off offset:128
	s_nop 0
	global_load_dwordx4 v[72:75], v[72:73], off offset:192
	v_addc_co_u32_e32 v135, vcc, 0, v131, vcc
	v_mfma_f32_16x16x32_bf16 v[76:79], v[24:27], v[8:11], v[60:63]
	s_cmpk_gt_u32 s30, 0x17f
	s_cselect_b64 s[14:15], -1, 0
	s_and_b64 vcc, exec, s[14:15]
	v_mfma_f32_16x16x32_bf16 v[92:95], v[32:35], v[8:11], v[88:91]
	s_nop 2
	global_load_dwordx4 v[88:91], v[134:135], off offset:128
	global_load_dwordx4 v[60:63], v[134:135], off offset:192
	v_mfma_f32_16x16x32_bf16 v[96:99], v[40:43], v[8:11], v[96:99]
	s_cbranch_vccnz .LBB0_1063
	v_add_co_u32_e32 v16, vcc, 0x400000, v130
	s_nop 1
	v_addc_co_u32_e32 v17, vcc, 0, v131, vcc
	v_add_co_u32_e32 v24, vcc, 0x404000, v130
	s_nop 1
	v_addc_co_u32_e32 v25, vcc, 0, v131, vcc
	v_add_co_u32_e32 v32, vcc, 0x408000, v130
	s_nop 1
	v_addc_co_u32_e32 v33, vcc, 0, v131, vcc
	v_add_co_u32_e32 v40, vcc, 0x40c000, v130
	s_nop 1
	v_addc_co_u32_e32 v41, vcc, 0, v131, vcc
	global_load_dwordx4 v[4:7], v[128:129], off
	global_load_dwordx4 v[8:11], v[128:129], off offset:64
	global_load_dwordx4 v[12:15], v[16:17], off offset:256
	s_nop 0
	global_load_dwordx4 v[16:19], v[16:17], off offset:320
	s_nop 0
	global_load_dwordx4 v[20:23], v[24:25], off offset:256
	s_nop 0
	global_load_dwordx4 v[24:27], v[24:25], off offset:320
	s_nop 0
	global_load_dwordx4 v[28:31], v[32:33], off offset:256
	s_nop 0
	global_load_dwordx4 v[32:35], v[32:33], off offset:320
	s_nop 0
	global_load_dwordx4 v[36:39], v[40:41], off offset:256
	s_nop 0
	global_load_dwordx4 v[40:43], v[40:41], off offset:320
	s_waitcnt vmcnt(10)
	s_branch .Lglu_rb_b

; __device__ __forceinline__ float bf1(bf16 h) { return __uint_as_float((unsigned)h << 16); }
; __device__ __forceinline__ void gmlp_sample_item(LAS unsigned char* lds, int tid, int lane, int wave, int b, const bf16* VG, const bf16* UG,
;                                                  const float* w_s, const float* g_v, const float* b_v, const float* b_s, bf16* YCAT, float* vs_out) {
;     ...
; #pragma unroll
;     for (int j = 0; j < 4; ++j) { vv[j] = bf1(VG[(row0 + j) * GMW + c]); const float s1 = wave_sum(vv[j]), s2 = wave_sum(vv[j] * vv[j]); if (lane == 0) { red[wave * 8 + 2 * j] = s1; red[wave * 8 + 2 * j + 1] = s2; } }
;     __syncthreads();
.LBB0_1070:
	s_and_b64 vcc, exec, s[4:5]
	s_cbranch_vccz .LBB0_1046
	s_add_i32 s6, s26, 0xffffff80
	s_lshl_b32 s7, s6, 2
	s_ashr_i32 s44, s7, 31
	s_add_u32 s14, s7, 0x4000
	v_readlane_b32 s68, v252, 26
	v_readlane_b32 s28, v252, 4
	s_addc_u32 s15, s44, 0
	v_readlane_b32 s76, v252, 34
	v_readlane_b32 s77, v252, 35
	v_readlane_b32 s29, v252, 5
	s_lshl_b64 s[34:35], s[14:15], 10
	s_mov_b64 s[46:47], s[76:77]
	s_mov_b64 s[48:49], s[28:29]
	v_lshl_add_u64 v[4:5], v[108:109], 0, s[34:35]
	global_load_ushort v74, v[4:5], off offset:1024
	global_load_ushort v75, v[4:5], off offset:2048
	global_load_ushort v76, v[4:5], off offset:3072
	global_load_ushort v4, v[4:5], off
	s_nop 0
	global_load_dword v22, v[104:105], off
	global_load_dword v2, v[106:107], off
	v_and_b32_e32 v5, 32, v247
	v_cmp_eq_u32_e32 vcc, 0, v5
	v_and_b32_e32 v8, 16, v247
	v_cmp_eq_u32_e64 s[4:5], 0, v8
	v_readlane_b32 s69, v252, 27
	v_readlane_b32 s70, v252, 28
	v_readlane_b32 s71, v252, 29
	v_readlane_b32 s72, v252, 30
	v_readlane_b32 s73, v252, 31
	v_readlane_b32 s74, v252, 32
	v_readlane_b32 s75, v252, 33
	v_readlane_b32 s78, v252, 36
	v_readlane_b32 s79, v252, 37
	v_readlane_b32 s80, v252, 38
	v_readlane_b32 s81, v252, 39
	v_readlane_b32 s82, v252, 40
	v_readlane_b32 s83, v252, 41
	v_readlane_b32 s30, v252, 6
	v_readlane_b32 s31, v252, 7
	s_waitcnt vmcnt(0)
	v_lshlrev_b32_e32 v18, 16, v4
	v_mul_f32_e32 v19, v18, v18
	s_nop 0
	v_mov_b32_dpp v4, v18 quad_perm:[1,0,3,2] row_mask:0xf bank_mask:0xf bound_ctrl:1
	v_mov_b32_dpp v5, v19 quad_perm:[1,0,3,2] row_mask:0xf bank_mask:0xf bound_ctrl:1
	v_pk_add_f32 v[4:5], v[18:19], v[4:5]
	s_nop 1
	v_mov_b32_dpp v6, v4 quad_perm:[2,3,0,1] row_mask:0xf bank_mask:0xf bound_ctrl:1
	v_mov_b32_dpp v7, v5 quad_perm:[2,3,0,1] row_mask:0xf bank_mask:0xf bound_ctrl:1
	v_pk_add_f32 v[4:5], v[4:5], v[6:7]
	s_nop 1
	v_mov_b32_dpp v6, v4 row_half_mirror row_mask:0xf bank_mask:0xf bound_ctrl:1
	v_mov_b32_dpp v7, v5 row_half_mirror row_mask:0xf bank_mask:0xf bound_ctrl:1
	s_nop 0
	v_mov_b32_dpp v6, v6 quad_perm:[3,2,1,0] row_mask:0xf bank_mask:0xf bound_ctrl:1
	v_mov_b32_dpp v7, v7 quad_perm:[3,2,1,0] row_mask:0xf bank_mask:0xf bound_ctrl:1
	v_pk_add_f32 v[4:5], v[4:5], v[6:7]
	s_nop 1
	v_mov_b32_dpp v6, v4 row_ror:8 row_mask:0xf bank_mask:0xf bound_ctrl:1
	v_mov_b32_dpp v7, v5 row_ror:8 row_mask:0xf bank_mask:0xf bound_ctrl:1
	v_pk_add_f32 v[4:5], v[4:5], v[6:7]
	s_nop 0
	v_mov_b32_e32 v6, v4
	v_mov_b32_e32 v9, v4
	v_mov_b32_e32 v7, v5
	v_mov_b32_e32 v10, v5
	v_permlane16_swap_b32_e32 v6, v9
	s_nop 0
	v_permlane16_swap_b32_e32 v7, v10
	v_cndmask_b32_e64 v7, v7, v10, s[4:5]
	v_cndmask_b32_e64 v6, v6, v9, s[4:5]
	v_pk_add_f32 v[4:5], v[4:5], v[6:7]
	s_nop 0
	v_mov_b32_e32 v6, v4
	v_mov_b32_e32 v7, v4
	v_mov_b32_e32 v8, v5
	v_mov_b32_e32 v9, v5
	v_permlane32_swap_b32_e32 v6, v7
	s_nop 0
	v_permlane32_swap_b32_e32 v8, v9
	s_and_saveexec_b64 s[26:27], s[2:3]
	v_cndmask_b32_e32 v9, v8, v9, vcc
	v_cndmask_b32_e32 v8, v6, v7, vcc
	v_pk_add_f32 v[4:5], v[4:5], v[8:9]
	v_mov_b32_e32 v6, s58
	ds_write_b64 v6, v[4:5]
	s_or_b64 exec, exec, s[26:27]
	s_add_u32 s26, s7, 0x4001
	s_addc_u32 s27, s44, 0
	s_lshl_b64 s[40:41], s[26:27], 10
	v_lshl_add_u64 v[4:5], v[108:109], 0, s[40:41]
	v_lshlrev_b32_e32 v16, 16, v74
	v_mul_f32_e32 v17, v16, v16
	s_nop 0
	v_mov_b32_dpp v4, v16 quad_perm:[1,0,3,2] row_mask:0xf bank_mask:0xf bound_ctrl:1
	v_mov_b32_dpp v5, v17 quad_perm:[1,0,3,2] row_mask:0xf bank_mask:0xf bound_ctrl:1
	v_pk_add_f32 v[4:5], v[16:17], v[4:5]
	s_nop 1
	v_mov_b32_dpp v6, v4 quad_perm:[2,3,0,1] row_mask:0xf bank_mask:0xf bound_ctrl:1
	v_mov_b32_dpp v7, v5 quad_perm:[2,3,0,1] row_mask:0xf bank_mask:0xf bound_ctrl:1
	v_pk_add_f32 v[4:5], v[4:5], v[6:7]
	s_nop 1
	v_mov_b32_dpp v6, v4 row_half_mirror row_mask:0xf bank_mask:0xf bound_ctrl:1
	v_mov_b32_dpp v7, v5 row_half_mirror row_mask:0xf bank_mask:0xf bound_ctrl:1
	s_nop 0
	v_mov_b32_dpp v6, v6 quad_perm:[3,2,1,0] row_mask:0xf bank_mask:0xf bound_ctrl:1
	v_mov_b32_dpp v7, v7 quad_perm:[3,2,1,0] row_mask:0xf bank_mask:0xf bound_ctrl:1
	v_pk_add_f32 v[4:5], v[4:5], v[6:7]
	s_nop 1
	v_mov_b32_dpp v6, v4 row_ror:8 row_mask:0xf bank_mask:0xf bound_ctrl:1
	v_mov_b32_dpp v7, v5 row_ror:8 row_mask:0xf bank_mask:0xf bound_ctrl:1
	v_pk_add_f32 v[4:5], v[4:5], v[6:7]
	s_nop 0
	v_mov_b32_e32 v6, v4
	v_mov_b32_e32 v8, v4
	v_mov_b32_e32 v7, v5
	v_mov_b32_e32 v9, v5
	v_permlane16_swap_b32_e32 v6, v8
	s_nop 0
	v_permlane16_swap_b32_e32 v7, v9
	v_cndmask_b32_e64 v7, v7, v9, s[4:5]
	v_cndmask_b32_e64 v6, v6, v8, s[4:5]
	v_pk_add_f32 v[4:5], v[4:5], v[6:7]
	s_nop 0
	v_mov_b32_e32 v6, v4
	v_mov_b32_e32 v7, v4
	v_mov_b32_e32 v8, v5
	v_mov_b32_e32 v9, v5
	v_permlane32_swap_b32_e32 v6, v7
	s_nop 0
	v_permlane32_swap_b32_e32 v8, v9
	s_and_saveexec_b64 s[28:29], s[2:3]
	v_cndmask_b32_e32 v9, v8, v9, vcc
	v_cndmask_b32_e32 v8, v6, v7, vcc
	v_pk_add_f32 v[4:5], v[4:5], v[8:9]
	v_mov_b32_e32 v6, s58
	ds_write_b64 v6, v[4:5] offset:8
	s_or_b64 exec, exec, s[28:29]
	s_add_u32 s28, s7, 0x4002
	s_addc_u32 s29, s44, 0
	s_lshl_b64 s[42:43], s[28:29], 10
	v_lshl_add_u64 v[4:5], v[108:109], 0, s[42:43]
	v_lshlrev_b32_e32 v12, 16, v75
	v_mul_f32_e32 v13, v12, v12
	s_nop 0
	v_mov_b32_dpp v4, v12 quad_perm:[1,0,3,2] row_mask:0xf bank_mask:0xf bound_ctrl:1
	v_mov_b32_dpp v5, v13 quad_perm:[1,0,3,2] row_mask:0xf bank_mask:0xf bound_ctrl:1
	v_pk_add_f32 v[4:5], v[12:13], v[4:5]
	s_nop 1
	v_mov_b32_dpp v6, v4 quad_perm:[2,3,0,1] row_mask:0xf bank_mask:0xf bound_ctrl:1
	v_mov_b32_dpp v7, v5 quad_perm:[2,3,0,1] row_mask:0xf bank_mask:0xf bound_ctrl:1
	v_pk_add_f32 v[4:5], v[4:5], v[6:7]
	s_nop 1
	v_mov_b32_dpp v6, v4 row_half_mirror row_mask:0xf bank_mask:0xf bound_ctrl:1
; __device__ __forceinline__ float bf1(bf16 h) { return __uint_as_float((unsigned)h << 16); }
; __device__ __forceinline__ void gmlp_sample_item(LAS unsigned char* lds, int tid, int lane, int wave, int b, const bf16* VG, const bf16* UG,
;                                                  const float* w_s, const float* g_v, const float* b_v, const float* b_s, bf16* YCAT, float* vs_out) {
;     ...
;     for (int j = 0; j < 4; ++j) { vv[j] = bf1(VG[(row0 + j) * GMW + c]); const float s1 = wave_sum(vv[j]), s2 = wave_sum(vv[j] * vv[j]); if (lane == 0) { red[wave * 8 + 2 * j] = s1; red[wave * 8 + 2 * j + 1] = s2; } }
;     __syncthreads();
; #pragma unroll
;     for (int j = 0; j < 4; ++j) { float s1 = 0.f, s2 = 0.f;
; #pragma unroll
;         for (int w = 0; w < 8; ++w) { s1 += red[w * 8 + 2 * j]; s2 += red[w * 8 + 2 * j + 1]; }
;         const float m = s1 * (1.0f / 512.0f); float var = s2 * (1.0f / 512.0f) - m * m; var = var > 0.f ? var : 0.f;
;         vn[j] = (vv[j] - m) * __builtin_amdgcn_rsqf(var + NORM_EPS) * gv + bv;
;         vs_out[((size_t)b * DECS + j) * GMW + c] = vn[j]; }
	v_mov_b32_dpp v7, v5 row_half_mirror row_mask:0xf bank_mask:0xf bound_ctrl:1
	s_nop 0
	v_mov_b32_dpp v6, v6 quad_perm:[3,2,1,0] row_mask:0xf bank_mask:0xf bound_ctrl:1
	v_mov_b32_dpp v7, v7 quad_perm:[3,2,1,0] row_mask:0xf bank_mask:0xf bound_ctrl:1
	v_pk_add_f32 v[4:5], v[4:5], v[6:7]
	s_nop 1
	v_mov_b32_dpp v6, v4 row_ror:8 row_mask:0xf bank_mask:0xf bound_ctrl:1
	v_mov_b32_dpp v7, v5 row_ror:8 row_mask:0xf bank_mask:0xf bound_ctrl:1
	v_pk_add_f32 v[4:5], v[4:5], v[6:7]
	s_nop 0
	v_mov_b32_e32 v6, v4
	v_mov_b32_e32 v8, v4
	v_mov_b32_e32 v7, v5
	v_mov_b32_e32 v9, v5
	v_permlane16_swap_b32_e32 v6, v8
	s_nop 0
	v_permlane16_swap_b32_e32 v7, v9
	v_cndmask_b32_e64 v7, v7, v9, s[4:5]
	v_cndmask_b32_e64 v6, v6, v8, s[4:5]
	v_pk_add_f32 v[4:5], v[4:5], v[6:7]
	s_nop 0
	v_mov_b32_e32 v6, v4
	v_mov_b32_e32 v7, v4
	v_mov_b32_e32 v8, v5
	v_mov_b32_e32 v9, v5
	v_permlane32_swap_b32_e32 v6, v7
	s_nop 0
	v_permlane32_swap_b32_e32 v8, v9
	s_and_saveexec_b64 s[30:31], s[2:3]
	v_cndmask_b32_e32 v9, v8, v9, vcc
	v_cndmask_b32_e32 v8, v6, v7, vcc
	v_pk_add_f32 v[4:5], v[4:5], v[8:9]
	v_mov_b32_e32 v6, s58
	ds_write_b64 v6, v[4:5] offset:16
	s_or_b64 exec, exec, s[30:31]
	s_add_u32 s30, s7, 0x4003
	s_addc_u32 s31, s44, 0
	s_lshl_b64 s[44:45], s[30:31], 10
	v_lshl_add_u64 v[4:5], v[108:109], 0, s[44:45]
	v_lshlrev_b32_e32 v14, 16, v76
	v_mul_f32_e32 v15, v14, v14
	s_nop 0
	v_mov_b32_dpp v4, v14 quad_perm:[1,0,3,2] row_mask:0xf bank_mask:0xf bound_ctrl:1
	v_mov_b32_dpp v5, v15 quad_perm:[1,0,3,2] row_mask:0xf bank_mask:0xf bound_ctrl:1
	v_pk_add_f32 v[4:5], v[14:15], v[4:5]
	s_nop 1
	v_mov_b32_dpp v6, v4 quad_perm:[2,3,0,1] row_mask:0xf bank_mask:0xf bound_ctrl:1
	v_mov_b32_dpp v7, v5 quad_perm:[2,3,0,1] row_mask:0xf bank_mask:0xf bound_ctrl:1
	v_pk_add_f32 v[4:5], v[4:5], v[6:7]
	s_nop 1
	v_mov_b32_dpp v6, v4 row_half_mirror row_mask:0xf bank_mask:0xf bound_ctrl:1
	v_mov_b32_dpp v7, v5 row_half_mirror row_mask:0xf bank_mask:0xf bound_ctrl:1
	s_nop 0
	v_mov_b32_dpp v6, v6 quad_perm:[3,2,1,0] row_mask:0xf bank_mask:0xf bound_ctrl:1
	v_mov_b32_dpp v7, v7 quad_perm:[3,2,1,0] row_mask:0xf bank_mask:0xf bound_ctrl:1
	v_pk_add_f32 v[4:5], v[4:5], v[6:7]
	s_nop 1
	v_mov_b32_dpp v6, v4 row_ror:8 row_mask:0xf bank_mask:0xf bound_ctrl:1
	v_mov_b32_dpp v7, v5 row_ror:8 row_mask:0xf bank_mask:0xf bound_ctrl:1
	v_pk_add_f32 v[4:5], v[4:5], v[6:7]
	s_nop 0
	v_mov_b32_e32 v6, v4
	v_mov_b32_e32 v8, v4
	v_mov_b32_e32 v7, v5
	v_mov_b32_e32 v9, v5
	v_permlane16_swap_b32_e32 v6, v8
	s_nop 0
	v_permlane16_swap_b32_e32 v7, v9
	v_cndmask_b32_e64 v7, v7, v9, s[4:5]
	v_cndmask_b32_e64 v6, v6, v8, s[4:5]
	v_pk_add_f32 v[4:5], v[4:5], v[6:7]
	s_nop 0
	v_mov_b32_e32 v6, v4
	v_mov_b32_e32 v7, v4
	v_mov_b32_e32 v8, v5
	v_mov_b32_e32 v9, v5
	v_permlane32_swap_b32_e32 v6, v7
	s_nop 0
	v_permlane32_swap_b32_e32 v8, v9
	s_and_saveexec_b64 s[50:51], s[2:3]
	v_cndmask_b32_e32 v9, v8, v9, vcc
	v_cndmask_b32_e32 v8, v6, v7, vcc
	v_pk_add_f32 v[4:5], v[4:5], v[8:9]
	v_mov_b32_e32 v6, s58
	ds_write_b64 v6, v[4:5] offset:24
	s_or_b64 exec, exec, s[50:51]
	s_waitcnt lgkmcnt(0)
	s_barrier
	ds_read_b128 v[24:27], v3
	ds_read_b128 v[28:31], v3 offset:32
	ds_read_b128 v[32:35], v3 offset:64
	ds_read_b128 v[36:39], v3 offset:96
	ds_read_b128 v[40:43], v3 offset:128
	ds_read_b128 v[44:47], v3 offset:160
	ds_read_b128 v[48:51], v3 offset:192
	ds_read_b128 v[52:55], v3 offset:224
	s_mov_b32 s38, 0x3b000000
	s_waitcnt lgkmcnt(7)
	v_pk_add_f32 v[4:5], v[24:25], 0 op_sel_hi:[1,0]
	s_add_u32 s46, s46, s22
	s_waitcnt lgkmcnt(6)
	v_pk_add_f32 v[4:5], v[4:5], v[28:29]
	s_addc_u32 s47, s47, s23
	s_waitcnt lgkmcnt(5)
	v_pk_add_f32 v[4:5], v[4:5], v[32:33]
	s_add_u32 s48, s48, s24
	s_waitcnt lgkmcnt(4)
	v_pk_add_f32 v[4:5], v[4:5], v[36:37]
	s_addc_u32 s49, s49, s25
	s_waitcnt lgkmcnt(3)
	v_pk_add_f32 v[4:5], v[4:5], v[40:41]
	s_ashr_i32 s7, s6, 31
	s_waitcnt lgkmcnt(2)
	v_pk_add_f32 v[4:5], v[4:5], v[44:45]
	s_lshl_b64 s[6:7], s[6:7], 13
	s_waitcnt lgkmcnt(1)
	v_pk_add_f32 v[4:5], v[4:5], v[48:49]
	s_add_u32 s6, s48, s6
	s_waitcnt lgkmcnt(0)
	v_pk_add_f32 v[4:5], v[4:5], v[52:53]
	s_addc_u32 s7, s49, s7
	v_pk_mul_f32 v[24:25], v[4:5], s[38:39] op_sel_hi:[1,0]
	v_lshl_add_u64 v[56:57], v[160:161], 2, s[6:7]
	v_fma_f32 v4, -v24, v24, v25
	v_sub_f32_e32 v15, v18, v24
	v_pk_add_f32 v[24:25], v[26:27], 0 op_sel_hi:[1,0]
	v_max_f32_e32 v4, 0, v4
	v_pk_add_f32 v[24:25], v[24:25], v[30:31]
	v_add_f32_e32 v4, 0x358637bd, v4
	v_pk_add_f32 v[24:25], v[24:25], v[34:35]
	v_rsq_f32_e32 v13, v4
	v_pk_add_f32 v[24:25], v[24:25], v[38:39]
	ds_read_b128 v[4:7], v3 offset:16
	ds_read_b128 v[8:11], v3 offset:48
	v_pk_add_f32 v[24:25], v[24:25], v[42:43]
	s_mov_b64 s[6:7], 0x4640000
	v_pk_add_f32 v[24:25], v[24:25], v[46:47]
	v_lshl_add_u64 v[20:21], v[56:57], 0, s[6:7]
	v_pk_add_f32 v[24:25], v[24:25], v[50:51]
	s_mov_b32 s6, 0x4641000
	v_pk_add_f32 v[24:25], v[24:25], v[54:55]
	v_mul_f32_e32 v13, v15, v13
	v_pk_mul_f32 v[28:29], v[24:25], s[38:39] op_sel_hi:[1,0]
	ds_read_b128 v[24:27], v3 offset:80
	v_add_co_u32_e64 v18, s[6:7], s6, v56
	v_fma_f32 v15, v22, v13, v2
	s_nop 0
	v_addc_co_u32_e64 v19, s[6:7], 0, v57, s[6:7]
	s_waitcnt lgkmcnt(2)
	v_pk_add_f32 v[4:5], v[4:5], 0 op_sel_hi:[1,0]
	global_store_dword v[18:19], v15, off offset:-4096
	s_waitcnt lgkmcnt(1)
	v_pk_add_f32 v[4:5], v[4:5], v[8:9]
	v_fma_f32 v13, -v28, v28, v29
	v_sub_f32_e32 v16, v16, v28
	s_waitcnt lgkmcnt(0)
	v_pk_add_f32 v[4:5], v[4:5], v[24:25]
	ds_read_b128 v[28:31], v3 offset:112
	ds_read_b128 v[32:35], v3 offset:144
	ds_read_b128 v[36:39], v3 offset:176
	ds_read_b128 v[40:43], v3 offset:208
	ds_read_b128 v[44:47], v3 offset:240
	s_waitcnt lgkmcnt(4)
; __device__ __forceinline__ float bf1(bf16 h) { return __uint_as_float((unsigned)h << 16); }
; __device__ __forceinline__ void gmlp_sample_item(LAS unsigned char* lds, int tid, int lane, int wave, int b, const bf16* VG, const bf16* UG,
;                                                  const float* w_s, const float* g_v, const float* b_v, const float* b_s, bf16* YCAT, float* vs_out) {
;     ...
;         const float m = s1 * (1.0f / 512.0f); float var = s2 * (1.0f / 512.0f) - m * m; var = var > 0.f ? var : 0.f;
;         vn[j] = (vv[j] - m) * __builtin_amdgcn_rsqf(var + NORM_EPS) * gv + bv;
;         vs_out[((size_t)b * DECS + j) * GMW + c] = vn[j]; }
;     __syncthreads();
; #pragma unroll
;     for (int t = 0; t < 4; ++t) { float mix = b_s[h * CHUNK + t];
; #pragma unroll
;         for (int s = 0; s <= t; ++s) mix += w_s[((size_t)h * CHUNK + t) * CHUNK + s] * vn[s];
;         y[t] = bf1(UG[(row0 + t) * GMW + c]) * mix; }
; #pragma unroll
;     for (int t = 0; t < 4; ++t) { const float s = wave_sum(y[t] * y[t]); if (lane == 0) red[wave * 4 + t] = s; }
	v_pk_add_f32 v[4:5], v[4:5], v[28:29]
	v_max_f32_e32 v13, 0, v13
	s_waitcnt lgkmcnt(3)
	v_pk_add_f32 v[4:5], v[4:5], v[32:33]
	v_add_f32_e32 v13, 0x358637bd, v13
	s_waitcnt lgkmcnt(2)
	v_pk_add_f32 v[4:5], v[4:5], v[36:37]
	v_rsq_f32_e32 v13, v13
	s_waitcnt lgkmcnt(1)
	v_pk_add_f32 v[4:5], v[4:5], v[40:41]
	v_mul_f32_e32 v13, v16, v13
	s_waitcnt lgkmcnt(0)
	v_pk_add_f32 v[4:5], v[4:5], v[44:45]
	v_fma_f32 v23, v22, v13, v2
	v_pk_mul_f32 v[4:5], v[4:5], s[38:39] op_sel_hi:[1,0]
	global_store_dword v[20:21], v23, off offset:2048
	v_fma_f32 v5, -v4, v4, v5
	v_max_f32_e32 v5, 0, v5
	v_add_f32_e32 v5, 0x358637bd, v5
	v_rsq_f32_e32 v5, v5
	v_sub_f32_e32 v4, v12, v4
	v_mul_f32_e32 v8, v4, v5
	v_pk_add_f32 v[4:5], v[6:7], 0 op_sel_hi:[1,0]
	v_fma_f32 v20, v22, v8, v2
	v_pk_add_f32 v[4:5], v[4:5], v[10:11]
	global_store_dword v[18:19], v20, off
	v_pk_add_f32 v[4:5], v[4:5], v[26:27]
	v_lshl_add_u64 v[8:9], s[46:47], 0, v[110:111]
	v_pk_add_f32 v[4:5], v[4:5], v[30:31]
	v_lshl_add_u64 v[10:11], v[112:113], 0, s[34:35]
	v_pk_add_f32 v[4:5], v[4:5], v[34:35]
	s_nop 0
	v_pk_add_f32 v[4:5], v[4:5], v[38:39]
	s_nop 0
	v_pk_add_f32 v[4:5], v[4:5], v[42:43]
	s_nop 0
	v_pk_add_f32 v[4:5], v[4:5], v[46:47]
	s_nop 0
	v_pk_mul_f32 v[4:5], v[4:5], s[38:39] op_sel_hi:[1,0]
	s_nop 0
	v_fma_f32 v5, -v4, v4, v5
	v_max_f32_e32 v5, 0, v5
	v_add_f32_e32 v5, 0x358637bd, v5
	v_rsq_f32_e32 v5, v5
	v_sub_f32_e32 v4, v14, v4
	v_mul_f32_e32 v4, v4, v5
	v_fmac_f32_e32 v2, v22, v4
	global_store_dword v[18:19], v2, off offset:2048
	s_barrier
	global_load_dwordx4 v[4:7], v[114:115], off
	global_load_dword v24, v[8:9], off
	global_load_ushort v25, v[10:11], off
	global_load_dwordx2 v[16:17], v[8:9], off offset:512
	v_lshl_add_u64 v[10:11], v[112:113], 0, s[40:41]
	global_load_ushort v22, v[10:11], off
	global_load_dwordx3 v[12:14], v[8:9], off offset:1024
	v_lshl_add_u64 v[10:11], v[112:113], 0, s[42:43]
	v_lshl_add_u64 v[18:19], v[112:113], 0, s[44:45]
	global_load_ushort v21, v[10:11], off
	s_nop 0
	global_load_dwordx4 v[8:11], v[8:9], off offset:1536
	s_waitcnt vmcnt(6)
	v_fma_f32 v4, v15, v24, v4
	global_load_ushort v19, v[18:19], off
	s_waitcnt vmcnt(6)
	v_lshlrev_b32_e32 v18, 16, v25
	v_mul_f32_e32 v18, v4, v18
	v_mul_f32_e32 v4, v18, v18
	s_nop 1
	v_mov_b32_dpp v4, v4 quad_perm:[1,0,3,2] row_mask:0xf bank_mask:0xf bound_ctrl:1
	v_fmac_f32_e32 v4, v18, v18
	s_nop 1
	v_add_f32_dpp v4, v4, v4 quad_perm:[2,3,0,1] row_mask:0xf bank_mask:0xf bound_ctrl:1
	s_nop 1
	v_mov_b32_dpp v24, v4 row_half_mirror row_mask:0xf bank_mask:0xf bound_ctrl:1
	s_nop 1
	v_add_f32_dpp v4, v24, v4 quad_perm:[3,2,1,0] row_mask:0xf bank_mask:0xf bound_ctrl:1
	s_nop 1
	v_add_f32_dpp v4, v4, v4 row_ror:8 row_mask:0xf bank_mask:0xf bound_ctrl:1
	v_mov_b32_e32 v24, v4
	v_mov_b32_e32 v25, v4
	s_nop 1
	v_permlane16_swap_b32_e32 v24, v25
	v_cndmask_b32_e64 v24, v24, v25, s[4:5]
	v_add_f32_e32 v4, v4, v24
	v_mov_b32_e32 v24, v4
	v_mov_b32_e32 v25, v4
	s_nop 1
	v_permlane32_swap_b32_e32 v24, v25
	s_and_saveexec_b64 s[6:7], s[2:3]
	v_cndmask_b32_e32 v24, v24, v25, vcc
	s_add_i32 s34, s58, s59
	v_add_f32_e32 v4, v4, v24
	v_mov_b32_e32 v24, s34
	ds_write_b32 v24, v4
	s_or_b64 exec, exec, s[6:7]
	s_waitcnt vmcnt(5)
	v_fma_f32 v4, v15, v16, v5
	v_fmac_f32_e32 v4, v23, v17
	s_waitcnt vmcnt(4)
	v_lshlrev_b32_e32 v5, 16, v22
	v_mul_f32_e32 v5, v4, v5
	v_mul_f32_e32 v4, v5, v5
	s_nop 1
	v_mov_b32_dpp v4, v4 quad_perm:[1,0,3,2] row_mask:0xf bank_mask:0xf bound_ctrl:1
	v_fmac_f32_e32 v4, v5, v5
	s_nop 1
	v_add_f32_dpp v4, v4, v4 quad_perm:[2,3,0,1] row_mask:0xf bank_mask:0xf bound_ctrl:1
	s_nop 1
	v_mov_b32_dpp v16, v4 row_half_mirror row_mask:0xf bank_mask:0xf bound_ctrl:1
	s_nop 1
	v_add_f32_dpp v4, v16, v4 quad_perm:[3,2,1,0] row_mask:0xf bank_mask:0xf bound_ctrl:1
	s_nop 1
	v_add_f32_dpp v4, v4, v4 row_ror:8 row_mask:0xf bank_mask:0xf bound_ctrl:1
	v_mov_b32_e32 v16, v4
	v_mov_b32_e32 v17, v4
	s_nop 1
	v_permlane16_swap_b32_e32 v16, v17
	v_cndmask_b32_e64 v16, v16, v17, s[4:5]
	v_add_f32_e32 v4, v4, v16
	v_mov_b32_e32 v16, v4
	v_mov_b32_e32 v17, v4
	s_nop 1
	v_permlane32_swap_b32_e32 v16, v17
	s_and_saveexec_b64 s[6:7], s[2:3]
	v_cndmask_b32_e32 v16, v16, v17, vcc
	s_add_i32 s34, s58, s59
	v_add_f32_e32 v4, v4, v16
	v_mov_b32_e32 v16, s34
	ds_write_b32 v16, v4 offset:4
	s_or_b64 exec, exec, s[6:7]
	s_waitcnt vmcnt(3)
	v_fma_f32 v4, v15, v12, v6
	v_fmac_f32_e32 v4, v23, v13
	v_fmac_f32_e32 v4, v20, v14
	s_waitcnt vmcnt(2)
	v_lshlrev_b32_e32 v6, 16, v21
	v_mul_f32_e32 v4, v4, v6
	v_mul_f32_e32 v6, v4, v4
	s_nop 1
	v_mov_b32_dpp v6, v6 quad_perm:[1,0,3,2] row_mask:0xf bank_mask:0xf bound_ctrl:1
	v_fmac_f32_e32 v6, v4, v4
	s_nop 1
	v_add_f32_dpp v6, v6, v6 quad_perm:[2,3,0,1] row_mask:0xf bank_mask:0xf bound_ctrl:1
	s_nop 1
	v_mov_b32_dpp v12, v6 row_half_mirror row_mask:0xf bank_mask:0xf bound_ctrl:1
	s_nop 1
	v_add_f32_dpp v6, v12, v6 quad_perm:[3,2,1,0] row_mask:0xf bank_mask:0xf bound_ctrl:1
	s_nop 1
	v_add_f32_dpp v6, v6, v6 row_ror:8 row_mask:0xf bank_mask:0xf bound_ctrl:1
	v_mov_b32_e32 v12, v6
	v_mov_b32_e32 v13, v6
	s_nop 1
	v_permlane16_swap_b32_e32 v12, v13
	v_cndmask_b32_e64 v12, v12, v13, s[4:5]
	v_add_f32_e32 v6, v6, v12
	v_mov_b32_e32 v12, v6
	v_mov_b32_e32 v13, v6
	s_nop 1
	v_permlane32_swap_b32_e32 v12, v13
	s_and_saveexec_b64 s[6:7], s[2:3]
	v_cndmask_b32_e32 v12, v12, v13, vcc
	s_add_i32 s34, s58, s59
	v_add_f32_e32 v6, v6, v12
	v_mov_b32_e32 v12, s34
	ds_write_b32 v12, v6 offset:8
	s_or_b64 exec, exec, s[6:7]
	s_waitcnt vmcnt(1)
	v_fmac_f32_e32 v7, v15, v8
	v_fmac_f32_e32 v7, v23, v9
	v_fmac_f32_e32 v7, v20, v10
	v_fmac_f32_e32 v7, v2, v11
	s_waitcnt vmcnt(0)
	v_lshlrev_b32_e32 v2, 16, v19
	v_mul_f32_e32 v2, v7, v2
	v_mul_f32_e32 v6, v2, v2
	s_nop 1
	v_mov_b32_dpp v6, v6 quad_perm:[1,0,3,2] row_mask:0xf bank_mask:0xf bound_ctrl:1
	v_fmac_f32_e32 v6, v2, v2
	s_nop 1
	v_add_f32_dpp v6, v6, v6 quad_perm:[2,3,0,1] row_mask:0xf bank_mask:0xf bound_ctrl:1
	s_nop 1
	v_mov_b32_dpp v7, v6 row_half_mirror row_mask:0xf bank_mask:0xf bound_ctrl:1
	s_nop 1
	v_add_f32_dpp v6, v7, v6 quad_perm:[3,2,1,0] row_mask:0xf bank_mask:0xf bound_ctrl:1
	s_nop 1
	v_add_f32_dpp v6, v6, v6 row_ror:8 row_mask:0xf bank_mask:0xf bound_ctrl:1
	v_mov_b32_e32 v7, v6
	v_mov_b32_e32 v8, v6
	s_nop 1
	v_permlane16_swap_b32_e32 v7, v8
	v_cndmask_b32_e64 v7, v7, v8, s[4:5]
	v_add_f32_e32 v6, v6, v7
	v_mov_b32_e32 v7, v6
	v_mov_b32_e32 v8, v6
	s_nop 1
	v_permlane32_swap_b32_e32 v7, v8
	s_and_saveexec_b64 s[4:5], s[2:3]
	s_cbranch_execz .LBB0_1045
	v_cndmask_b32_e32 v7, v7, v8, vcc
	s_add_i32 s6, s58, s59
	v_add_f32_e32 v6, v6, v7
	v_mov_b32_e32 v7, s6
	ds_write_b32 v7, v6 offset:12
	s_branch .LBB0_1045
